# baseline (speedup 1.0000x reference)
; __device__ __forceinline__ void final_phase(float* out, const bf16_t* HB, const unsigned long long* ss, const float* fw) {
;     int tid_ = threadIdx.x; asm volatile("" : "+v"(tid_)); const int lane = tid_ & 63, w = tid_ >> 6;
;     for (int r = blockIdx.x * 8 + w; r < NREAL; r += gridDim.x * 8) {
;         const float rstd = __builtin_amdgcn_rsqf((float)ss[r] * (1.f / 16777216.f) * (1.f / 2048.f) + 1e-6f);
; #pragma unroll
;         for (int i = 0; i < 4; ++i) {
;             const int c = 8 * lane + 512 * i;
;             const u32x4 hv = *(const u32x4*)(HB + (size_t)r * 2048 + c);
;             float f[8]; unpack8(hv, f);
;             const f32x4 g0 = *(const f32x4*)(fw + c), g1 = *(const f32x4*)(fw + c + 4);
;             f32x4 o0, o1;
; #pragma unroll
;             for (int j = 0; j < 4; ++j) { o0[j] = f[j] * rstd * g0[j]; o1[j] = f[4 + j] * rstd * g1[j]; }
;             *(f32x4*)(out + (size_t)r * 2048 + c) = o0; *(f32x4*)(out + (size_t)r * 2048 + c + 4) = o1;
;         }
;     }
; }
.LBB0_119:
	v_ashrrev_i32_e32 v1, 31, v0
	v_lshl_add_u64 v[14:15], v[0:1], 3, s[70:71]
	global_load_dwordx2 v[26:27], v[14:15], off
	v_lshlrev_b64 v[14:15], 12, v[0:1]
	v_lshl_add_u64 v[28:29], v[8:9], 0, v[14:15]
	global_load_dwordx4 v[14:17], v[28:29], off nt
	global_load_dwordx4 v[18:21], v[2:3], off
	global_load_dwordx4 v[22:25], v[2:3], off offset:16
	v_lshlrev_b64 v[30:31], 13, v[0:1]
	v_lshl_add_u64 v[30:31], s[66:67], 0, v[30:31]
	v_lshl_add_u64 v[32:33], v[30:31], 0, v[188:189]
	v_mov_b32_e32 v13, v189
	v_add_u32_e32 v0, s3, v0
	v_cmp_lt_i32_e32 vcc, s94, v0
	s_or_b64 s[4:5], vcc, s[4:5]
	s_waitcnt vmcnt(3)
	v_ffbh_u32_e32 v1, v27
	v_min_u32_e32 v1, 32, v1
	v_lshlrev_b64 v[26:27], v1, v[26:27]
	v_min_u32_e32 v11, 1, v26
	v_or_b32_e32 v11, v27, v11
	v_cvt_f32_u32_e32 v11, v11
	v_sub_u32_e32 v1, 32, v1
	s_waitcnt vmcnt(2)
	v_lshlrev_b32_e32 v34, 16, v14
	v_and_b32_e32 v35, 0xffff0000, v14
	v_ldexp_f32 v1, v11, v1
	v_mul_f32_e32 v1, 0x33800000, v1
	v_fmamk_f32 v1, v1, 0x3a000000, v227
	v_rsq_f32_e32 v26, v1
	v_lshlrev_b32_e32 v14, 16, v15
	v_and_b32_e32 v15, 0xffff0000, v15
	v_lshlrev_b32_e32 v36, 16, v16
	v_and_b32_e32 v37, 0xffff0000, v16
	v_lshlrev_b32_e32 v16, 16, v17
	v_and_b32_e32 v17, 0xffff0000, v17
	v_pk_mul_f32 v[34:35], v[26:27], v[34:35] op_sel_hi:[0,1]
	v_pk_mul_f32 v[38:39], v[26:27], v[14:15] op_sel_hi:[0,1]
	v_pk_mul_f32 v[36:37], v[26:27], v[36:37] op_sel_hi:[0,1]
	v_pk_mul_f32 v[40:41], v[26:27], v[16:17] op_sel_hi:[0,1]
	s_waitcnt vmcnt(1)
	v_pk_mul_f32 v[14:15], v[18:19], v[34:35]
	v_pk_mul_f32 v[16:17], v[20:21], v[38:39]
	s_waitcnt vmcnt(0)
	v_pk_mul_f32 v[18:19], v[22:23], v[36:37]
	v_pk_mul_f32 v[20:21], v[24:25], v[40:41]
	global_store_dwordx4 v[32:33], v[14:17], off
	global_store_dwordx4 v[32:33], v[18:21], off offset:16
	global_load_dwordx4 v[14:17], v[28:29], off offset:1024 nt
	s_nop 0
	global_load_dwordx4 v[18:21], v[2:3], off offset:2048
	global_load_dwordx4 v[22:25], v[2:3], off offset:2064
	v_mov_b32_e32 v11, v189
	s_waitcnt vmcnt(2)
	v_lshlrev_b32_e32 v34, 16, v14
	v_and_b32_e32 v35, 0xffff0000, v14
	v_lshlrev_b32_e32 v14, 16, v15
	v_and_b32_e32 v15, 0xffff0000, v15
	v_lshlrev_b32_e32 v36, 16, v16
	v_and_b32_e32 v37, 0xffff0000, v16
	v_lshlrev_b32_e32 v16, 16, v17
	v_and_b32_e32 v17, 0xffff0000, v17
	v_pk_mul_f32 v[34:35], v[26:27], v[34:35] op_sel_hi:[0,1]
	v_pk_mul_f32 v[38:39], v[26:27], v[14:15] op_sel_hi:[0,1]
	v_pk_mul_f32 v[36:37], v[26:27], v[36:37] op_sel_hi:[0,1]
	v_pk_mul_f32 v[40:41], v[26:27], v[16:17] op_sel_hi:[0,1]
	s_waitcnt vmcnt(1)
	v_pk_mul_f32 v[14:15], v[18:19], v[34:35]
	v_pk_mul_f32 v[16:17], v[20:21], v[38:39]
	s_waitcnt vmcnt(0)
	v_pk_mul_f32 v[18:19], v[22:23], v[36:37]
	v_pk_mul_f32 v[20:21], v[24:25], v[40:41]
	global_store_dwordx4 v[32:33], v[14:17], off offset:2048
	global_store_dwordx4 v[32:33], v[18:21], off offset:2064
	global_load_dwordx4 v[14:17], v[28:29], off offset:2048 nt
	s_nop 0
	global_load_dwordx4 v[18:21], v[4:5], off
	global_load_dwordx4 v[22:25], v[4:5], off offset:16
	v_lshl_add_u64 v[32:33], v[30:31], 0, v[10:11]
	s_waitcnt vmcnt(2)
	v_lshlrev_b32_e32 v34, 16, v14
	v_and_b32_e32 v35, 0xffff0000, v14
	v_lshlrev_b32_e32 v14, 16, v15
	v_and_b32_e32 v15, 0xffff0000, v15
	v_lshlrev_b32_e32 v36, 16, v16
	v_and_b32_e32 v37, 0xffff0000, v16
	v_lshlrev_b32_e32 v16, 16, v17
	v_and_b32_e32 v17, 0xffff0000, v17
	v_pk_mul_f32 v[34:35], v[26:27], v[34:35] op_sel_hi:[0,1]
	v_pk_mul_f32 v[38:39], v[26:27], v[14:15] op_sel_hi:[0,1]
	v_pk_mul_f32 v[36:37], v[26:27], v[36:37] op_sel_hi:[0,1]
	v_pk_mul_f32 v[40:41], v[26:27], v[16:17] op_sel_hi:[0,1]
	s_waitcnt vmcnt(1)
	v_pk_mul_f32 v[14:15], v[18:19], v[34:35]
	v_pk_mul_f32 v[16:17], v[20:21], v[38:39]
	s_waitcnt vmcnt(0)
	v_pk_mul_f32 v[18:19], v[22:23], v[36:37]
	v_pk_mul_f32 v[20:21], v[24:25], v[40:41]
	global_store_dwordx4 v[32:33], v[14:17], off
	global_store_dwordx4 v[32:33], v[18:21], off offset:16
	global_load_dwordx4 v[14:17], v[28:29], off offset:3072 nt
	s_nop 0
	global_load_dwordx4 v[18:21], v[6:7], off
	global_load_dwordx4 v[22:25], v[6:7], off offset:16
	v_lshl_add_u64 v[28:29], v[30:31], 0, v[12:13]
	s_waitcnt vmcnt(2)
	v_lshlrev_b32_e32 v30, 16, v14
	v_and_b32_e32 v31, 0xffff0000, v14
	v_lshlrev_b32_e32 v14, 16, v15
	v_and_b32_e32 v15, 0xffff0000, v15
	v_lshlrev_b32_e32 v32, 16, v16
	v_and_b32_e32 v33, 0xffff0000, v16
	v_lshlrev_b32_e32 v16, 16, v17
	v_and_b32_e32 v17, 0xffff0000, v17
	v_pk_mul_f32 v[30:31], v[26:27], v[30:31] op_sel_hi:[0,1]
	v_pk_mul_f32 v[34:35], v[26:27], v[14:15] op_sel_hi:[0,1]
	v_pk_mul_f32 v[32:33], v[26:27], v[32:33] op_sel_hi:[0,1]
	v_pk_mul_f32 v[26:27], v[26:27], v[16:17] op_sel_hi:[0,1]
	s_waitcnt vmcnt(1)
	v_pk_mul_f32 v[14:15], v[18:19], v[30:31]
	v_pk_mul_f32 v[16:17], v[20:21], v[34:35]
	s_waitcnt vmcnt(0)
	v_pk_mul_f32 v[18:19], v[22:23], v[32:33]
	v_pk_mul_f32 v[20:21], v[24:25], v[26:27]
	global_store_dwordx4 v[28:29], v[14:17], off
	global_store_dwordx4 v[28:29], v[18:21], off offset:16
	s_andn2_b64 exec, exec, s[4:5]
	s_cbranch_execnz .LBB0_119

; #define PG8_STAGE(bufoff, gbase, voff) do { _Pragma("unroll") for (int _i = 0; _i < 2; ++_i) \
;         __builtin_amdgcn_global_load_lds((const unsigned*)((const char*)(gbase) + (voff)[_i]), (PG8_LAS unsigned*)(lds + (bufoff) + ldsw + _i * 8192), 16, 0, 0); } while (0)
; #define PG8_LDA(dst, b, h) do { _Pragma("unroll") for (int m = 0; m < 4; ++m) _Pragma("unroll") for (int k = 0; k < 2; ++k) dst[m][k] = *(const PG8_LAS bf16x8*)(lds + PG8_SA(b, h) + aoff + m * 2048 + k * 1024); } while (0)
; #define PG8_LDB(dst, b, h) do { _Pragma("unroll") for (int n = 0; n < 2; ++n) _Pragma("unroll") for (int k = 0; k < 2; ++k) dst[n][k] = *(const PG8_LAS bf16x8*)(lds + PG8_SB(b, h) + boff + n * 2048 + k * 1024); } while (0)
; #define PG8_MMA(ai, bj, At, Bt) do { __builtin_amdgcn_s_setprio(1); _Pragma("unroll") for (int m = 0; m < 4; ++m) _Pragma("unroll") for (int n = 0; n < 2; ++n) _Pragma("unroll") for (int k = 0; k < 2; ++k) \
;         acc[ai][bj][m][n] = __builtin_amdgcn_mfma_f32_16x16x32_bf16(Bt[n][k], At[m][k], acc[ai][bj][m][n], 0, 0, 0); __builtin_amdgcn_s_setprio(0); } while (0)
; #define PG8_WAIT_V(n) asm volatile("s_waitcnt vmcnt(" #n ")" ::: "memory")
; #define PG8_WAIT_L(n) asm volatile("s_waitcnt lgkmcnt(" #n ")" ::: "memory")
; #define PG8_BAR __builtin_amdgcn_s_barrier()
; #define PG8_SCHED __builtin_amdgcn_sched_barrier(0)
; template <class Epi, class Sched, bool ALIGN_EPI = false, bool SP2 = false>
; __device__ __forceinline__ void gemm_phase(PG8_LAS unsigned char* lds, const Gemm g, const Sched& S, const Epi& E) {
;     ...
;             PG8_LDB(B0, 0, 0); PG8_LDB(B1, 0, 1); PG8_SCHED; PG8_LDA(At, 0, 0); PG8_STAGE(PG8_SA(1, 1), a1 + hstep, voffA);
;             PG8_WAIT_V(8); PG8_WAIT_L(0); PG8_BAR; PG8_MMA(0, 0, At, B0); PG8_MMA(0, 1, At, B1); PG8_BAR; PG8_SCHED;
;             PG8_LDA(At, 0, 1); PG8_STAGE(PG8_SB(0, 0), b2, voffB); PG8_STAGE(PG8_SB(0, 1), b2 + hstep, voffB); PG8_STAGE(PG8_SA(0, 0), a2, voffA);
;             PG8_WAIT_V(8); PG8_WAIT_L(0); PG8_BAR; PG8_MMA(1, 0, At, B0); PG8_MMA(1, 1, At, B1); PG8_BAR; PG8_SCHED;
.LBB0_205:
	s_add_u32 s36, s68, 0xfff80080
	s_addc_u32 s37, s69, -1
	s_add_i32 s38, 0, 0x10000
	s_cmp_eq_u32 s89, 28
	s_cselect_b32 s73, s9, s37
	s_cselect_b32 s72, s61, s36
	s_cselect_b32 s71, s59, s88
	s_cselect_b32 s70, s87, s3
	s_add_i32 s39, 0, 0x14000
	ds_read_b128 v[80:83], v204
	ds_read_b128 v[88:91], v204 offset:1024
	ds_read_b128 v[104:107], v204 offset:2048
	ds_read_b128 v[108:111], v204 offset:3072
	ds_read_b128 v[128:131], v204 offset:16384
	ds_read_b128 v[132:135], v204 offset:17408
	ds_read_b128 v[152:155], v204 offset:18432
	ds_read_b128 v[156:159], v204 offset:19456
	s_add_i32 m0, s67, 0xc000
	ds_read_b128 v[160:163], v240
	ds_read_b128 v[164:167], v240 offset:1024
	ds_read_b128 v[168:171], v240 offset:2048
	ds_read_b128 v[172:175], v240 offset:3072
	ds_read_b128 v[176:179], v240 offset:4096
	ds_read_b128 v[180:183], v240 offset:5120
	ds_read_b128 v[184:187], v240 offset:6144
	ds_read_b128 v[200:203], v240 offset:7168
	global_load_lds_dwordx4 v196, s[68:69]
	s_add_i32 m0, s67, 0xe000
	s_nop 0
	global_load_lds_dwordx4 v198, s[68:69]
	s_waitcnt vmcnt(8)
	s_waitcnt lgkmcnt(0)
	s_barrier
	s_setprio 1
	s_waitcnt lgkmcnt(0)
	v_mfma_f32_16x16x32_bf16 v[148:151], v[80:83], v[160:163], v[148:151]
	v_mfma_f32_16x16x32_bf16 v[148:151], v[88:91], v[164:167], v[148:151]
	v_mfma_f32_16x16x32_bf16 v[144:147], v[104:107], v[160:163], v[144:147]
	v_mfma_f32_16x16x32_bf16 v[144:147], v[108:111], v[164:167], v[144:147]
	v_mfma_f32_16x16x32_bf16 v[124:127], v[80:83], v[168:171], v[124:127]
	v_mfma_f32_16x16x32_bf16 v[124:127], v[88:91], v[172:175], v[124:127]
	v_mfma_f32_16x16x32_bf16 v[120:123], v[104:107], v[168:171], v[120:123]
	v_mfma_f32_16x16x32_bf16 v[120:123], v[108:111], v[172:175], v[120:123]
	v_mfma_f32_16x16x32_bf16 v[100:103], v[80:83], v[176:179], v[100:103]
	v_mfma_f32_16x16x32_bf16 v[100:103], v[88:91], v[180:183], v[100:103]
	v_mfma_f32_16x16x32_bf16 v[96:99], v[104:107], v[176:179], v[96:99]
	v_mfma_f32_16x16x32_bf16 v[96:99], v[108:111], v[180:183], v[96:99]
	v_mfma_f32_16x16x32_bf16 v[76:79], v[80:83], v[184:187], v[76:79]
	v_mfma_f32_16x16x32_bf16 v[76:79], v[88:91], v[200:203], v[76:79]
	v_mfma_f32_16x16x32_bf16 v[72:75], v[104:107], v[184:187], v[72:75]
	v_mfma_f32_16x16x32_bf16 v[72:75], v[108:111], v[200:203], v[72:75]
	s_setprio 0
	s_setprio 1
	v_mfma_f32_16x16x32_bf16 v[140:143], v[128:131], v[160:163], v[140:143]
	v_mfma_f32_16x16x32_bf16 v[140:143], v[132:135], v[164:167], v[140:143]
	v_mfma_f32_16x16x32_bf16 v[136:139], v[152:155], v[160:163], v[136:139]
	v_mfma_f32_16x16x32_bf16 v[136:139], v[156:159], v[164:167], v[136:139]
	v_mfma_f32_16x16x32_bf16 v[116:119], v[128:131], v[168:171], v[116:119]
	v_mfma_f32_16x16x32_bf16 v[116:119], v[132:135], v[172:175], v[116:119]
	v_mfma_f32_16x16x32_bf16 v[112:115], v[152:155], v[168:171], v[112:115]
	v_mfma_f32_16x16x32_bf16 v[112:115], v[156:159], v[172:175], v[112:115]
	v_mfma_f32_16x16x32_bf16 v[92:95], v[128:131], v[176:179], v[92:95]
	v_mfma_f32_16x16x32_bf16 v[92:95], v[132:135], v[180:183], v[92:95]
	v_mfma_f32_16x16x32_bf16 v[84:87], v[152:155], v[176:179], v[84:87]
	v_mfma_f32_16x16x32_bf16 v[84:87], v[156:159], v[180:183], v[84:87]
	v_mfma_f32_16x16x32_bf16 v[68:71], v[128:131], v[184:187], v[68:71]
	v_mfma_f32_16x16x32_bf16 v[68:71], v[132:135], v[200:203], v[68:71]
	v_mfma_f32_16x16x32_bf16 v[64:67], v[152:155], v[184:187], v[64:67]
	v_mfma_f32_16x16x32_bf16 v[64:67], v[156:159], v[200:203], v[64:67]
	s_setprio 0
	s_barrier
	s_add_i32 s36, s38, s75
	s_mov_b32 m0, s36
	ds_read_b128 v[160:163], v240 offset:16384
	ds_read_b128 v[164:167], v240 offset:17408
	ds_read_b128 v[168:171], v240 offset:18432
	ds_read_b128 v[172:175], v240 offset:19456
	ds_read_b128 v[176:179], v240 offset:20480
	ds_read_b128 v[180:183], v240 offset:21504
	ds_read_b128 v[184:187], v240 offset:22528
	ds_read_b128 v[200:203], v240 offset:23552
	global_load_lds_dwordx4 v188, s[70:71]
	s_add_i32 m0, s36, 0x2000
	s_add_u32 s36, s70, 0x80000
	s_addc_u32 s37, s71, 0
	s_add_i32 s38, s39, s75
	global_load_lds_dwordx4 v194, s[70:71]
	s_mov_b32 m0, s38
	s_nop 0
	global_load_lds_dwordx4 v188, s[36:37]
	s_add_i32 m0, s38, 0x2000
	s_nop 0
	global_load_lds_dwordx4 v194, s[36:37]
	s_mov_b32 m0, s67
	s_nop 0
	global_load_lds_dwordx4 v188, s[72:73]
	s_mov_b32 m0, s76
	s_nop 0
	global_load_lds_dwordx4 v194, s[72:73]
	s_waitcnt vmcnt(8)
	s_waitcnt lgkmcnt(0)
	s_barrier
	s_setprio 1
	s_waitcnt lgkmcnt(0)
	v_mfma_f32_16x16x32_bf16 v[60:63], v[80:83], v[160:163], v[60:63]
	v_mfma_f32_16x16x32_bf16 v[60:63], v[88:91], v[164:167], v[60:63]
	v_mfma_f32_16x16x32_bf16 v[56:59], v[104:107], v[160:163], v[56:59]
	v_mfma_f32_16x16x32_bf16 v[56:59], v[108:111], v[164:167], v[56:59]
	v_mfma_f32_16x16x32_bf16 v[44:47], v[80:83], v[168:171], v[44:47]
	v_mfma_f32_16x16x32_bf16 v[44:47], v[88:91], v[172:175], v[44:47]
	v_mfma_f32_16x16x32_bf16 v[40:43], v[104:107], v[168:171], v[40:43]
	v_mfma_f32_16x16x32_bf16 v[40:43], v[108:111], v[172:175], v[40:43]
	v_mfma_f32_16x16x32_bf16 v[28:31], v[80:83], v[176:179], v[28:31]
	v_mfma_f32_16x16x32_bf16 v[28:31], v[88:91], v[180:183], v[28:31]
	v_mfma_f32_16x16x32_bf16 v[24:27], v[104:107], v[176:179], v[24:27]
	v_mfma_f32_16x16x32_bf16 v[24:27], v[108:111], v[180:183], v[24:27]
	v_mfma_f32_16x16x32_bf16 v[12:15], v[80:83], v[184:187], v[12:15]
	v_mfma_f32_16x16x32_bf16 v[12:15], v[88:91], v[200:203], v[12:15]
	v_mfma_f32_16x16x32_bf16 v[8:11], v[104:107], v[184:187], v[8:11]
	v_mfma_f32_16x16x32_bf16 v[8:11], v[108:111], v[200:203], v[8:11]
	s_setprio 0
	s_setprio 1
	v_mfma_f32_16x16x32_bf16 v[52:55], v[128:131], v[160:163], v[52:55]
	v_mfma_f32_16x16x32_bf16 v[52:55], v[132:135], v[164:167], v[52:55]
	v_mfma_f32_16x16x32_bf16 v[48:51], v[152:155], v[160:163], v[48:51]
	v_mfma_f32_16x16x32_bf16 v[48:51], v[156:159], v[164:167], v[48:51]
	v_mfma_f32_16x16x32_bf16 v[36:39], v[128:131], v[168:171], v[36:39]
	v_mfma_f32_16x16x32_bf16 v[36:39], v[132:135], v[172:175], v[36:39]
	v_mfma_f32_16x16x32_bf16 v[32:35], v[152:155], v[168:171], v[32:35]
	v_mfma_f32_16x16x32_bf16 v[32:35], v[156:159], v[172:175], v[32:35]
	v_mfma_f32_16x16x32_bf16 v[20:23], v[128:131], v[176:179], v[20:23]
	v_mfma_f32_16x16x32_bf16 v[20:23], v[132:135], v[180:183], v[20:23]
	v_mfma_f32_16x16x32_bf16 v[16:19], v[152:155], v[176:179], v[16:19]
	v_mfma_f32_16x16x32_bf16 v[16:19], v[156:159], v[180:183], v[16:19]
	v_mfma_f32_16x16x32_bf16 v[4:7], v[128:131], v[184:187], v[4:7]
	v_mfma_f32_16x16x32_bf16 v[4:7], v[132:135], v[200:203], v[4:7]
	v_mfma_f32_16x16x32_bf16 v[0:3], v[152:155], v[184:187], v[0:3]
	v_mfma_f32_16x16x32_bf16 v[0:3], v[156:159], v[200:203], v[0:3]
	s_setprio 0
	s_barrier
; #define PG8_STAGE(bufoff, gbase, voff) do { _Pragma("unroll") for (int _i = 0; _i < 2; ++_i) \
;         __builtin_amdgcn_global_load_lds((const unsigned*)((const char*)(gbase) + (voff)[_i]), (PG8_LAS unsigned*)(lds + (bufoff) + ldsw + _i * 8192), 16, 0, 0); } while (0)
; #define PG8_LDA(dst, b, h) do { _Pragma("unroll") for (int m = 0; m < 4; ++m) _Pragma("unroll") for (int k = 0; k < 2; ++k) dst[m][k] = *(const PG8_LAS bf16x8*)(lds + PG8_SA(b, h) + aoff + m * 2048 + k * 1024); } while (0)
; #define PG8_LDB(dst, b, h) do { _Pragma("unroll") for (int n = 0; n < 2; ++n) _Pragma("unroll") for (int k = 0; k < 2; ++k) dst[n][k] = *(const PG8_LAS bf16x8*)(lds + PG8_SB(b, h) + boff + n * 2048 + k * 1024); } while (0)
; #define PG8_MMA(ai, bj, At, Bt) do { __builtin_amdgcn_s_setprio(1); _Pragma("unroll") for (int m = 0; m < 4; ++m) _Pragma("unroll") for (int n = 0; n < 2; ++n) _Pragma("unroll") for (int k = 0; k < 2; ++k) \
;         acc[ai][bj][m][n] = __builtin_amdgcn_mfma_f32_16x16x32_bf16(Bt[n][k], At[m][k], acc[ai][bj][m][n], 0, 0, 0); __builtin_amdgcn_s_setprio(0); } while (0)
; #define PG8_WAIT_V(n) asm volatile("s_waitcnt vmcnt(" #n ")" ::: "memory")
; #define PG8_WAIT_L(n) asm volatile("s_waitcnt lgkmcnt(" #n ")" ::: "memory")
; #define PG8_BAR __builtin_amdgcn_s_barrier()
; #define PG8_SCHED __builtin_amdgcn_sched_barrier(0)
; template <class Epi, class Sched, bool ALIGN_EPI = false, bool SP2 = false>
; __device__ __forceinline__ void gemm_phase(PG8_LAS unsigned char* lds, const Gemm g, const Sched& S, const Epi& E) {
;     ...
;             PG8_LDB(B0, 1, 0); PG8_LDB(B1, 1, 1); PG8_SCHED; PG8_LDA(At, 1, 0); PG8_STAGE(PG8_SA(0, 1), a2 + hstep, voffA);
;             PG8_WAIT_V(8); PG8_WAIT_L(0); PG8_BAR; PG8_MMA(0, 0, At, B0); PG8_MMA(0, 1, At, B1); PG8_BAR; PG8_SCHED;
;             PG8_LDA(At, 1, 1); PG8_STAGE(PG8_SB(1, 0), b3, voffB); PG8_STAGE(PG8_SB(1, 1), b3 + hstep, voffB); PG8_STAGE(PG8_SA(1, 0), a3, voffA);
;             PG8_WAIT_V(8); PG8_WAIT_L(0); PG8_BAR; PG8_MMA(1, 0, At, B0); PG8_MMA(1, 1, At, B1); PG8_BAR; PG8_SCHED;
	s_add_i32 s38, 0, 0x18000
	s_add_i32 s39, 0, 0x1c000
	ds_read_b128 v[80:83], v204 offset:32768
	ds_read_b128 v[88:91], v204 offset:33792
	ds_read_b128 v[104:107], v204 offset:34816
	ds_read_b128 v[108:111], v204 offset:35840
	ds_read_b128 v[128:131], v204 offset:49152
	ds_read_b128 v[132:135], v204 offset:50176
	ds_read_b128 v[152:155], v204 offset:51200
	ds_read_b128 v[156:159], v204 offset:52224
	s_add_u32 s36, s72, 0x80000
	s_addc_u32 s37, s73, 0
	s_mov_b32 m0, s77
	ds_read_b128 v[160:163], v240 offset:32768
	ds_read_b128 v[164:167], v240 offset:33792
	ds_read_b128 v[168:171], v240 offset:34816
	ds_read_b128 v[172:175], v240 offset:35840
	ds_read_b128 v[176:179], v240 offset:36864
	ds_read_b128 v[180:183], v240 offset:37888
	ds_read_b128 v[184:187], v240 offset:38912
	ds_read_b128 v[200:203], v240 offset:39936
	global_load_lds_dwordx4 v188, s[36:37]
	s_mov_b32 m0, s78
	s_nop 0
	global_load_lds_dwordx4 v194, s[36:37]
	s_waitcnt vmcnt(8)
	s_waitcnt lgkmcnt(0)
	s_barrier
	s_setprio 1
	s_waitcnt lgkmcnt(0)
	v_mfma_f32_16x16x32_bf16 v[148:151], v[80:83], v[160:163], v[148:151]
	v_mfma_f32_16x16x32_bf16 v[148:151], v[88:91], v[164:167], v[148:151]
	v_mfma_f32_16x16x32_bf16 v[144:147], v[104:107], v[160:163], v[144:147]
	v_mfma_f32_16x16x32_bf16 v[144:147], v[108:111], v[164:167], v[144:147]
	v_mfma_f32_16x16x32_bf16 v[124:127], v[80:83], v[168:171], v[124:127]
	v_mfma_f32_16x16x32_bf16 v[124:127], v[88:91], v[172:175], v[124:127]
	v_mfma_f32_16x16x32_bf16 v[120:123], v[104:107], v[168:171], v[120:123]
	v_mfma_f32_16x16x32_bf16 v[120:123], v[108:111], v[172:175], v[120:123]
	v_mfma_f32_16x16x32_bf16 v[100:103], v[80:83], v[176:179], v[100:103]
	v_mfma_f32_16x16x32_bf16 v[100:103], v[88:91], v[180:183], v[100:103]
	v_mfma_f32_16x16x32_bf16 v[96:99], v[104:107], v[176:179], v[96:99]
	v_mfma_f32_16x16x32_bf16 v[96:99], v[108:111], v[180:183], v[96:99]
	v_mfma_f32_16x16x32_bf16 v[76:79], v[80:83], v[184:187], v[76:79]
	v_mfma_f32_16x16x32_bf16 v[76:79], v[88:91], v[200:203], v[76:79]
	v_mfma_f32_16x16x32_bf16 v[72:75], v[104:107], v[184:187], v[72:75]
	v_mfma_f32_16x16x32_bf16 v[72:75], v[108:111], v[200:203], v[72:75]
	s_setprio 0
	s_setprio 1
	v_mfma_f32_16x16x32_bf16 v[140:143], v[128:131], v[160:163], v[140:143]
	v_mfma_f32_16x16x32_bf16 v[140:143], v[132:135], v[164:167], v[140:143]
	v_mfma_f32_16x16x32_bf16 v[136:139], v[152:155], v[160:163], v[136:139]
	v_mfma_f32_16x16x32_bf16 v[136:139], v[156:159], v[164:167], v[136:139]
	v_mfma_f32_16x16x32_bf16 v[116:119], v[128:131], v[168:171], v[116:119]
	v_mfma_f32_16x16x32_bf16 v[116:119], v[132:135], v[172:175], v[116:119]
	v_mfma_f32_16x16x32_bf16 v[112:115], v[152:155], v[168:171], v[112:115]
	v_mfma_f32_16x16x32_bf16 v[112:115], v[156:159], v[172:175], v[112:115]
	v_mfma_f32_16x16x32_bf16 v[92:95], v[128:131], v[176:179], v[92:95]
	v_mfma_f32_16x16x32_bf16 v[92:95], v[132:135], v[180:183], v[92:95]
	v_mfma_f32_16x16x32_bf16 v[84:87], v[152:155], v[176:179], v[84:87]
	v_mfma_f32_16x16x32_bf16 v[84:87], v[156:159], v[180:183], v[84:87]
	v_mfma_f32_16x16x32_bf16 v[68:71], v[128:131], v[184:187], v[68:71]
	v_mfma_f32_16x16x32_bf16 v[68:71], v[132:135], v[200:203], v[68:71]
	v_mfma_f32_16x16x32_bf16 v[64:67], v[152:155], v[184:187], v[64:67]
	v_mfma_f32_16x16x32_bf16 v[64:67], v[156:159], v[200:203], v[64:67]
	s_setprio 0
	s_barrier
	s_add_i32 s36, s38, s75
	s_mov_b32 m0, s36
	ds_read_b128 v[160:163], v240 offset:49152
	ds_read_b128 v[164:167], v240 offset:50176
	ds_read_b128 v[168:171], v240 offset:51200
	ds_read_b128 v[172:175], v240 offset:52224
	ds_read_b128 v[176:179], v240 offset:53248
	ds_read_b128 v[180:183], v240 offset:54272
	ds_read_b128 v[184:187], v240 offset:55296
	ds_read_b128 v[200:203], v240 offset:56320
	s_add_u32 s100, s70, 0x80
	s_addc_u32 s101, s71, 0
	global_load_lds_dwordx4 v188, s[100:101]
	s_add_i32 m0, s36, 0x2000
	s_add_u32 s36, s70, 0x80080
	s_addc_u32 s37, s71, 0
	s_add_i32 s38, s39, s75
	global_load_lds_dwordx4 v194, s[100:101]
	s_mov_b32 m0, s38
	s_nop 0
	global_load_lds_dwordx4 v188, s[36:37]
	s_add_i32 m0, s38, 0x2000
	s_nop 0
	global_load_lds_dwordx4 v194, s[36:37]
	s_mov_b32 m0, s79
	s_nop 0
	s_add_u32 s100, s72, 0x80
	s_addc_u32 s101, s73, 0
	global_load_lds_dwordx4 v188, s[100:101]
	s_mov_b32 m0, s80
	s_nop 0
	global_load_lds_dwordx4 v194, s[100:101]
	s_waitcnt vmcnt(8)
	s_waitcnt lgkmcnt(0)
	s_barrier
; #define PG8_MMA(ai, bj, At, Bt) do { __builtin_amdgcn_s_setprio(1); _Pragma("unroll") for (int m = 0; m < 4; ++m) _Pragma("unroll") for (int n = 0; n < 2; ++n) _Pragma("unroll") for (int k = 0; k < 2; ++k) \
;         acc[ai][bj][m][n] = __builtin_amdgcn_mfma_f32_16x16x32_bf16(Bt[n][k], At[m][k], acc[ai][bj][m][n], 0, 0, 0); __builtin_amdgcn_s_setprio(0); } while (0)
; #define PG8_WAIT_V(n) asm volatile("s_waitcnt vmcnt(" #n ")" ::: "memory")
; #define PG8_WAIT_L(n) asm volatile("s_waitcnt lgkmcnt(" #n ")" ::: "memory")
; #define PG8_BAR __builtin_amdgcn_s_barrier()
; #define PG8_SCHED __builtin_amdgcn_sched_barrier(0)
;     __device__ __forceinline__ void operator()(const f32x4 (&acc)[2][2][4][2], const Unit& u, int wr, int wc, int fr, int fq) const {
;         const int r0 = u.pm * BM + wr * 64 + fr, c0 = u.pn * BM + 32 * wc + 8 * fq;
;         u32x4 hold[2][4][2];
; #pragma unroll
;         for (int ai = 0; ai < 2; ++ai)
; #pragma unroll
;             for (int m = 0; m < 4; ++m)
; #pragma unroll
;                 for (int bj = 0; bj < 2; ++bj) hold[ai][m][bj] = *(const u32x4*)(HB + (size_t)(r0 + ai * HALF + m * 16) * 2048 + c0 + bj * HALF);
; template <class Epi, class Sched, bool ALIGN_EPI = false, bool SP2 = false>
; __device__ __forceinline__ void gemm_phase(PG8_LAS unsigned char* lds, const Gemm g, const Sched& S, const Epi& E) {
;     ...
;             PG8_WAIT_V(8); PG8_WAIT_L(0); PG8_BAR; PG8_MMA(1, 0, At, B0); PG8_MMA(1, 1, At, B1); PG8_BAR; PG8_SCHED;
	s_setprio 1
	s_waitcnt lgkmcnt(0)
	v_mfma_f32_16x16x32_bf16 v[60:63], v[80:83], v[160:163], v[60:63]
	v_mfma_f32_16x16x32_bf16 v[60:63], v[88:91], v[164:167], v[60:63]
	v_mfma_f32_16x16x32_bf16 v[56:59], v[104:107], v[160:163], v[56:59]
	v_mfma_f32_16x16x32_bf16 v[56:59], v[108:111], v[164:167], v[56:59]
	v_mfma_f32_16x16x32_bf16 v[44:47], v[80:83], v[168:171], v[44:47]
	v_mfma_f32_16x16x32_bf16 v[44:47], v[88:91], v[172:175], v[44:47]
	v_mfma_f32_16x16x32_bf16 v[40:43], v[104:107], v[168:171], v[40:43]
	v_mfma_f32_16x16x32_bf16 v[40:43], v[108:111], v[172:175], v[40:43]
	v_mfma_f32_16x16x32_bf16 v[28:31], v[80:83], v[176:179], v[28:31]
	v_mfma_f32_16x16x32_bf16 v[28:31], v[88:91], v[180:183], v[28:31]
	v_mfma_f32_16x16x32_bf16 v[24:27], v[104:107], v[176:179], v[24:27]
	v_mfma_f32_16x16x32_bf16 v[24:27], v[108:111], v[180:183], v[24:27]
	v_mfma_f32_16x16x32_bf16 v[12:15], v[80:83], v[184:187], v[12:15]
	v_mfma_f32_16x16x32_bf16 v[12:15], v[88:91], v[200:203], v[12:15]
	v_mfma_f32_16x16x32_bf16 v[8:11], v[104:107], v[184:187], v[8:11]
	v_mfma_f32_16x16x32_bf16 v[8:11], v[108:111], v[200:203], v[8:11]
	s_setprio 0
	s_setprio 1
	v_mfma_f32_16x16x32_bf16 v[52:55], v[128:131], v[160:163], v[52:55]
	v_mfma_f32_16x16x32_bf16 v[52:55], v[132:135], v[164:167], v[52:55]
	v_mfma_f32_16x16x32_bf16 v[48:51], v[152:155], v[160:163], v[48:51]
	v_mfma_f32_16x16x32_bf16 v[48:51], v[156:159], v[164:167], v[48:51]
	v_mfma_f32_16x16x32_bf16 v[36:39], v[128:131], v[168:171], v[36:39]
	v_mfma_f32_16x16x32_bf16 v[36:39], v[132:135], v[172:175], v[36:39]
	v_mfma_f32_16x16x32_bf16 v[32:35], v[152:155], v[168:171], v[32:35]
	v_mfma_f32_16x16x32_bf16 v[32:35], v[156:159], v[172:175], v[32:35]
	v_mfma_f32_16x16x32_bf16 v[20:23], v[128:131], v[176:179], v[20:23]
	v_mfma_f32_16x16x32_bf16 v[20:23], v[132:135], v[180:183], v[20:23]
	v_mfma_f32_16x16x32_bf16 v[16:19], v[152:155], v[176:179], v[16:19]
	v_mfma_f32_16x16x32_bf16 v[16:19], v[156:159], v[180:183], v[16:19]
	v_mfma_f32_16x16x32_bf16 v[4:7], v[128:131], v[184:187], v[4:7]
	v_mfma_f32_16x16x32_bf16 v[4:7], v[132:135], v[200:203], v[4:7]
	v_mfma_f32_16x16x32_bf16 v[0:3], v[152:155], v[184:187], v[0:3]
	v_mfma_f32_16x16x32_bf16 v[0:3], v[156:159], v[200:203], v[0:3]
	s_setprio 0
	s_barrier
	s_add_i32 s89, s89, 2
	s_add_u32 s68, s68, 0x100
	s_addc_u32 s69, s69, 0
	s_add_u32 s3, s3, 0x100
	s_addc_u32 s88, s88, 0
	s_cmp_gt_u32 s89, 29
	s_cbranch_scc0 .LBB0_205
	v_lshl_add_u32 v202, s66, 8, v237
	v_lshl_or_b32 v200, s8, 8, v239
	v_ashrrev_i32_e32 v201, 31, v200
	v_ashrrev_i32_e32 v203, 31, v202
	v_or_b32_e32 v222, 16, v202
	v_lshl_add_u64 v[80:81], v[200:201], 1, s[34:35]
	v_lshlrev_b64 v[242:243], 12, v[202:203]
	v_ashrrev_i32_e32 v223, 31, v222
	v_or_b32_e32 v218, 32, v202
	v_lshl_add_u64 v[82:83], v[80:81], 0, v[242:243]
	v_lshlrev_b64 v[220:221], 12, v[222:223]
	v_ashrrev_i32_e32 v219, 31, v218
	v_or_b32_e32 v214, 48, v202
	global_load_dwordx4 v[228:231], v[82:83], off nt
	global_load_dwordx4 v[184:187], v[82:83], off offset:256 nt
	v_lshl_add_u64 v[82:83], v[80:81], 0, v[220:221]
	v_lshlrev_b64 v[216:217], 12, v[218:219]
	v_ashrrev_i32_e32 v215, 31, v214
	s_mov_b64 s[8:9], 0x80000
	global_load_dwordx4 v[180:183], v[82:83], off nt
	global_load_dwordx4 v[176:179], v[82:83], off offset:256 nt
	v_lshl_add_u64 v[82:83], v[80:81], 0, v[216:217]
	v_lshlrev_b64 v[212:213], 12, v[214:215]
	v_lshl_add_u64 v[210:211], v[242:243], 0, s[8:9]
	s_mov_b64 s[8:9], 0x90000
	global_load_dwordx4 v[172:175], v[82:83], off nt
	global_load_dwordx4 v[168:171], v[82:83], off offset:256 nt
	v_lshl_add_u64 v[82:83], v[80:81], 0, v[212:213]
	v_lshl_add_u64 v[208:209], v[242:243], 0, s[8:9]
	s_mov_b64 s[8:9], 0xa0000
	global_load_dwordx4 v[164:167], v[82:83], off nt
	global_load_dwordx4 v[160:163], v[82:83], off offset:256 nt
	v_lshl_add_u64 v[82:83], v[80:81], 0, v[210:211]
	v_lshl_add_u64 v[206:207], v[242:243], 0, s[8:9]
	s_mov_b64 s[8:9], 0xb0000
	global_load_dwordx4 v[156:159], v[82:83], off nt
	global_load_dwordx4 v[152:155], v[82:83], off offset:256 nt
	v_lshl_add_u64 v[82:83], v[80:81], 0, v[208:209]
	v_lshl_add_u64 v[204:205], v[242:243], 0, s[8:9]
	global_load_dwordx4 v[132:135], v[82:83], off nt
	global_load_dwordx4 v[128:131], v[82:83], off offset:256 nt
	v_lshl_add_u64 v[82:83], v[80:81], 0, v[206:207]
	v_lshl_add_u64 v[80:81], v[80:81], 0, v[204:205]
	global_load_dwordx4 v[108:111], v[82:83], off nt
	global_load_dwordx4 v[104:107], v[82:83], off offset:256 nt
	global_load_dwordx4 v[88:91], v[80:81], off nt
	s_nop 0
	global_load_dwordx4 v[80:83], v[80:81], off offset:256 nt
	v_lshl_add_u64 v[242:243], s[34:35], 0, v[242:243]
	s_and_b64 vcc, exec, s[56:57]
	s_cbranch_vccz .LBB0_208
	s_barrier
